# mlaproj: second WG of each CU walks its pool-diff streaming items (rounds 8..11) before its GEMM items (rounds 0..7)
# baseline (speedup 1.0000x reference)
.LBB0_314:
	v_readlane_b32 s24, v221, 62
	s_load_dword s0, s[52:53], 0x0
	s_waitcnt lgkmcnt(0)
	s_add_i32 s24, s0, s24
	s_getreg_b32 s0, hwreg(HW_REG_LDS_ALLOC, 0, 8)
	s_cmp_lg_u32 s0, 0
	s_movk_i32 s0, 0x17b7
	s_movk_i32 s1, 0x17ff
	s_cselect_b32 s0, s1, s0
	s_cmp_gt_i32 s24, s0
	s_cbranch_scc1 .LBB0_437
.LBB0_315:
	v_writelane_b32 v221, s24, 62
	s_getreg_b32 s0, hwreg(HW_REG_LDS_ALLOC, 0, 8)
	s_cmp_eq_u32 s0, 0
	s_cbranch_scc1 .Lmp_noremap
	s_add_i32 s0, s24, 0x1000
	s_add_i32 s1, s24, 0xfffff800
	s_cmpk_lt_u32 s24, 0x800
	s_cselect_b32 s24, s0, s1
	s_cmpk_gt_u32 s24, 0x17b7
	s_cbranch_scc1 .LBB0_314
